# FFN-in f0 mainloop: one 64-MFMA block per K-tile per wave half (2 barriers per K-tile), As half 1 re-read inside the block, per-half DMA schedule
# baseline (speedup 1.0000x reference)
; #define PG8_STAGE(bufoff, gbase, voff) do { _Pragma("unroll") for (int _i = 0; _i < 2; ++_i) \
;         __builtin_amdgcn_global_load_lds((const unsigned*)((const char*)(gbase) + (voff)[_i]), (PG8_LAS unsigned*)(lds + (bufoff) + ldsw + _i * 8192), 16, 0, 0); } while (0)
; #define PG8_LDA(dst, b, h) do { _Pragma("unroll") for (int m = 0; m < 4; ++m) _Pragma("unroll") for (int k = 0; k < 2; ++k) dst[m][k] = *(const PG8_LAS bf16x8*)(lds + PG8_SA(b, h) + aoff + m * 2048 + k * 1024); } while (0)
; #define PG8_LDB(dst, b, h) do { _Pragma("unroll") for (int n = 0; n < 2; ++n) _Pragma("unroll") for (int k = 0; k < 2; ++k) dst[n][k] = *(const PG8_LAS bf16x8*)(lds + PG8_SB(b, h) + boff + n * 2048 + k * 1024); } while (0)
; #define PG8_WAIT_V(n) asm volatile("s_waitcnt vmcnt(" #n ")" ::: "memory")
; template <class Epi, class Sched, bool ALIGN_EPI = false, bool SP2 = false>
; __device__ __forceinline__ void gemm_phase(PG8_LAS unsigned char* lds, const Gemm g, const Sched& S, const Epi& E) {
;     ...
;             const char* a1 = cA + (size_t)(t + 1) * kstA;
;             const char* a2 = last ? nA : cA + (size_t)(t + 2) * kstA; const char* b2 = last ? nB : cB + (size_t)(t + 2) * kstep;
;             const char* a3 = a2 + kstA; const char* b3 = b2 + kstep;
;             if (last && has_next) S.a_ready(nxt);
;             if constexpr (SP2) {
;             PG8_LDB(B0, 0, 0); PG8_LDB(B1, 0, 1); PG8_SCHED; PG8_LDA(At, 0, 0); PG8_STAGE(PG8_SA(1, 1), a1 + hstepA, voffA);
;             PG8_WAIT_V(8); PG8_WAIT_L(0); PG8_BAR; PG8_MMA(0, 0, At, B0); PG8_MMA(0, 1, At, B1); PG8_BAR; PG8_SCHED;
;             PG8_LDA(At, 0, 1); PG8_STAGE(PG8_SB(0, 0), b2, voffB); PG8_STAGE(PG8_SB(0, 1), b2 + hstepB, voffB); PG8_STAGE(PG8_SA(0, 0), a2, voffA);
;             PG8_WAIT_V(8); PG8_WAIT_L(0); PG8_BAR; PG8_MMA(1, 0, At, B0); PG8_MMA(1, 1, At, B1); PG8_BAR; PG8_SCHED;
;             PG8_LDB(B0, 1, 0); PG8_LDB(B1, 1, 1); PG8_SCHED; PG8_LDA(At, 1, 0); PG8_STAGE(PG8_SA(0, 1), a2 + hstepA, voffA);
;             PG8_WAIT_V(8); PG8_WAIT_L(0); PG8_BAR; PG8_MMA(0, 0, At, B0); PG8_MMA(0, 1, At, B1); PG8_BAR; PG8_SCHED;
;             PG8_LDA(At, 1, 1); PG8_STAGE(PG8_SB(1, 0), b3, voffB); PG8_STAGE(PG8_SB(1, 1), b3 + hstepB, voffB); PG8_STAGE(PG8_SA(1, 0), a3, voffA);
;             PG8_WAIT_V(8); PG8_WAIT_L(0); PG8_BAR; PG8_MMA(1, 0, At, B0); PG8_MMA(1, 1, At, B1); PG8_BAR; PG8_SCHED;
.LBB0_300:
	s_and_b64 vcc, exec, s[38:39]
	s_cbranch_vccz .Lmy_m64_0_w1_top
	s_branch .Lmy_m64_0_w0_first
.Lmy_m64_0_w0_top:
	s_add_i32 s58, s62, s3
	v_lshl_add_u64 v[222:223], v[222:223], 0, s[36:37]
	s_mov_b32 m0, s58
	s_nop 0
	global_load_lds_dwordx4 v[222:223], off
	s_add_i32 m0, s58, 0x2000
	s_add_u32 s56, s56, 0x80080
	v_lshl_add_u64 v[222:223], v[224:225], 0, s[36:37]
	s_addc_u32 s57, s57, 0
	s_add_i32 s58, s63, s3
	global_load_lds_dwordx4 v[222:223], off
	v_lshl_add_u64 v[222:223], s[56:57], 0, v[130:131]
	s_mov_b32 m0, s58
	s_nop 0
	global_load_lds_dwordx4 v[222:223], off
	v_lshl_add_u64 v[222:223], s[56:57], 0, v[134:135]
	s_add_i32 m0, s58, 0x2000
	s_nop 0
	global_load_lds_dwordx4 v[222:223], off
	v_lshl_add_u64 v[222:223], v[226:227], 0, s[36:37]
	s_mov_b32 m0, s44
	s_nop 0
	global_load_lds_dwordx4 v[222:223], off
	v_lshl_add_u64 v[222:223], v[228:229], 0, s[36:37]
	s_mov_b32 m0, s45
	s_nop 0
	global_load_lds_dwordx4 v[222:223], off
.Lmy_m64_0_w0_first:
	ds_read_b128 v[156:159], v152
	ds_read_b128 v[160:163], v152 offset:1024
	ds_read_b128 v[164:167], v152 offset:2048
	ds_read_b128 v[168:171], v152 offset:3072
	ds_read_b128 v[172:175], v153
	ds_read_b128 v[176:179], v153 offset:1024
	ds_read_b128 v[180:183], v153 offset:2048
	ds_read_b128 v[186:189], v153 offset:3072
	ds_read_b128 v[190:193], v154
	ds_read_b128 v[194:197], v154 offset:1024
	ds_read_b128 v[198:201], v154 offset:2048
	ds_read_b128 v[202:205], v154 offset:3072
	ds_read_b128 v[206:209], v154 offset:4096
	ds_read_b128 v[210:213], v154 offset:5120
	ds_read_b128 v[214:217], v154 offset:6144
	ds_read_b128 v[218:221], v154 offset:7168
	s_waitcnt vmcnt(6)
	s_waitcnt lgkmcnt(0)
	s_setprio 1
	s_barrier
	v_mfma_f32_16x16x32_bf16 v[124:127], v[156:159], v[190:193], v[124:127]
	v_mfma_f32_16x16x32_bf16 v[120:123], v[164:167], v[190:193], v[120:123]
	s_add_u32 s56, s50, 0xfff80080
	s_addc_u32 s57, s51, -1
	v_mfma_f32_16x16x32_bf16 v[116:119], v[172:175], v[190:193], v[116:119]
	s_cmp_eq_u32 s61, 28
	s_cselect_b32 s59, s4, s57
	v_mfma_f32_16x16x32_bf16 v[112:115], v[180:183], v[190:193], v[112:115]
	s_cselect_b32 s58, s5, s56
	s_cselect_b32 s57, s12, s43
	v_mfma_f32_16x16x32_bf16 v[124:127], v[160:163], v[194:197], v[124:127]
	s_cselect_b32 s56, s13, s41
	v_lshl_add_u64 v[222:223], s[50:51], 0, v[142:143]
	v_mfma_f32_16x16x32_bf16 v[120:123], v[168:171], v[194:197], v[120:123]
	s_add_i32 m0, s6, 0xc000
	s_nop 0
	global_load_lds_dwordx4 v[222:223], off
	v_mfma_f32_16x16x32_bf16 v[116:119], v[176:179], v[194:197], v[116:119]
	v_lshl_add_u64 v[222:223], s[50:51], 0, v[144:145]
	s_add_i32 m0, s6, 0xe000
	v_mfma_f32_16x16x32_bf16 v[112:115], v[186:189], v[194:197], v[112:115]
	s_nop 0
	global_load_lds_dwordx4 v[222:223], off
	ds_read_b128 v[190:193], v154 offset:16384
	ds_read_b128 v[194:197], v154 offset:17408
	v_mfma_f32_16x16x32_bf16 v[108:111], v[156:159], v[198:201], v[108:111]
	v_mfma_f32_16x16x32_bf16 v[104:107], v[164:167], v[198:201], v[104:107]
	v_mfma_f32_16x16x32_bf16 v[100:103], v[172:175], v[198:201], v[100:103]
	v_mfma_f32_16x16x32_bf16 v[96:99], v[180:183], v[198:201], v[96:99]
	v_mfma_f32_16x16x32_bf16 v[108:111], v[160:163], v[202:205], v[108:111]
	v_mfma_f32_16x16x32_bf16 v[104:107], v[168:171], v[202:205], v[104:107]
	v_mfma_f32_16x16x32_bf16 v[100:103], v[176:179], v[202:205], v[100:103]
	v_mfma_f32_16x16x32_bf16 v[96:99], v[186:189], v[202:205], v[96:99]
	ds_read_b128 v[198:201], v154 offset:18432
	ds_read_b128 v[202:205], v154 offset:19456
	v_mfma_f32_16x16x32_bf16 v[92:95], v[156:159], v[206:209], v[92:95]
	v_mfma_f32_16x16x32_bf16 v[88:91], v[164:167], v[206:209], v[88:91]
	v_mfma_f32_16x16x32_bf16 v[84:87], v[172:175], v[206:209], v[84:87]
	v_mfma_f32_16x16x32_bf16 v[80:83], v[180:183], v[206:209], v[80:83]
	v_mfma_f32_16x16x32_bf16 v[92:95], v[160:163], v[210:213], v[92:95]
	v_mfma_f32_16x16x32_bf16 v[88:91], v[168:171], v[210:213], v[88:91]
	v_mfma_f32_16x16x32_bf16 v[84:87], v[176:179], v[210:213], v[84:87]
	v_mfma_f32_16x16x32_bf16 v[80:83], v[186:189], v[210:213], v[80:83]
	ds_read_b128 v[206:209], v154 offset:20480
	ds_read_b128 v[210:213], v154 offset:21504
	v_mfma_f32_16x16x32_bf16 v[76:79], v[156:159], v[214:217], v[76:79]
	v_mfma_f32_16x16x32_bf16 v[72:75], v[164:167], v[214:217], v[72:75]
	v_mfma_f32_16x16x32_bf16 v[68:71], v[172:175], v[214:217], v[68:71]
	v_mfma_f32_16x16x32_bf16 v[64:67], v[180:183], v[214:217], v[64:67]
	v_mfma_f32_16x16x32_bf16 v[76:79], v[160:163], v[218:221], v[76:79]
	v_mfma_f32_16x16x32_bf16 v[72:75], v[168:171], v[218:221], v[72:75]
	v_mfma_f32_16x16x32_bf16 v[68:71], v[176:179], v[218:221], v[68:71]
	v_mfma_f32_16x16x32_bf16 v[64:67], v[186:189], v[218:221], v[64:67]
	ds_read_b128 v[214:217], v154 offset:22528
	ds_read_b128 v[218:221], v154 offset:23552
	s_waitcnt lgkmcnt(6)
	v_mfma_f32_16x16x32_bf16 v[60:63], v[156:159], v[190:193], v[60:63]
	v_mfma_f32_16x16x32_bf16 v[56:59], v[164:167], v[190:193], v[56:59]
	v_mfma_f32_16x16x32_bf16 v[52:55], v[172:175], v[190:193], v[52:55]
	v_mfma_f32_16x16x32_bf16 v[48:51], v[180:183], v[190:193], v[48:51]
	v_mfma_f32_16x16x32_bf16 v[60:63], v[160:163], v[194:197], v[60:63]
	v_mfma_f32_16x16x32_bf16 v[56:59], v[168:171], v[194:197], v[56:59]
	v_mfma_f32_16x16x32_bf16 v[52:55], v[176:179], v[194:197], v[52:55]
	v_mfma_f32_16x16x32_bf16 v[48:51], v[186:189], v[194:197], v[48:51]
	s_waitcnt lgkmcnt(4)
; #define PG8_STAGE(bufoff, gbase, voff) do { _Pragma("unroll") for (int _i = 0; _i < 2; ++_i) \
;         __builtin_amdgcn_global_load_lds((const unsigned*)((const char*)(gbase) + (voff)[_i]), (PG8_LAS unsigned*)(lds + (bufoff) + ldsw + _i * 8192), 16, 0, 0); } while (0)
; #define PG8_LDA(dst, b, h) do { _Pragma("unroll") for (int m = 0; m < 4; ++m) _Pragma("unroll") for (int k = 0; k < 2; ++k) dst[m][k] = *(const PG8_LAS bf16x8*)(lds + PG8_SA(b, h) + aoff + m * 2048 + k * 1024); } while (0)
; #define PG8_LDB(dst, b, h) do { _Pragma("unroll") for (int n = 0; n < 2; ++n) _Pragma("unroll") for (int k = 0; k < 2; ++k) dst[n][k] = *(const PG8_LAS bf16x8*)(lds + PG8_SB(b, h) + boff + n * 2048 + k * 1024); } while (0)
; #define PG8_MMA(ai, bj, At, Bt) do { __builtin_amdgcn_s_setprio(1); _Pragma("unroll") for (int m = 0; m < 4; ++m) _Pragma("unroll") for (int n = 0; n < 2; ++n) _Pragma("unroll") for (int k = 0; k < 2; ++k) \
;         acc[ai][bj][m][n] = __builtin_amdgcn_mfma_f32_16x16x32_bf16(Bt[n][k], At[m][k], acc[ai][bj][m][n], 0, 0, 0); __builtin_amdgcn_s_setprio(0); } while (0)
; #define PG8_WAIT_V(n) asm volatile("s_waitcnt vmcnt(" #n ")" ::: "memory")
; #define PG8_WAIT_L(n) asm volatile("s_waitcnt lgkmcnt(" #n ")" ::: "memory")
; #define PG8_BAR __builtin_amdgcn_s_barrier()
; #define PG8_SCHED __builtin_amdgcn_sched_barrier(0)
; template <class Epi, class Sched, bool ALIGN_EPI = false, bool SP2 = false>
; __device__ __forceinline__ void gemm_phase(PG8_LAS unsigned char* lds, const Gemm g, const Sched& S, const Epi& E) {
;     ...
;             PG8_WAIT_V(8); PG8_WAIT_L(0); PG8_BAR; PG8_MMA(0, 0, At, B0); PG8_MMA(0, 1, At, B1); PG8_BAR; PG8_SCHED;
;             PG8_LDA(At, 0, 1); PG8_STAGE(PG8_SB(0, 0), b2, voffB); PG8_STAGE(PG8_SB(0, 1), b2 + hstepB, voffB); PG8_STAGE(PG8_SA(0, 0), a2, voffA);
;             PG8_WAIT_V(8); PG8_WAIT_L(0); PG8_BAR; PG8_MMA(1, 0, At, B0); PG8_MMA(1, 1, At, B1); PG8_BAR; PG8_SCHED;
;             PG8_LDB(B0, 1, 0); PG8_LDB(B1, 1, 1); PG8_SCHED; PG8_LDA(At, 1, 0); PG8_STAGE(PG8_SA(0, 1), a2 + hstepA, voffA);
;             PG8_WAIT_V(8); PG8_WAIT_L(0); PG8_BAR; PG8_MMA(0, 0, At, B0); PG8_MMA(0, 1, At, B1); PG8_BAR; PG8_SCHED;
	v_mfma_f32_16x16x32_bf16 v[44:47], v[156:159], v[198:201], v[44:47]
	v_mfma_f32_16x16x32_bf16 v[40:43], v[164:167], v[198:201], v[40:43]
	v_mfma_f32_16x16x32_bf16 v[36:39], v[172:175], v[198:201], v[36:39]
	v_mfma_f32_16x16x32_bf16 v[32:35], v[180:183], v[198:201], v[32:35]
	v_mfma_f32_16x16x32_bf16 v[44:47], v[160:163], v[202:205], v[44:47]
	v_mfma_f32_16x16x32_bf16 v[40:43], v[168:171], v[202:205], v[40:43]
	v_mfma_f32_16x16x32_bf16 v[36:39], v[176:179], v[202:205], v[36:39]
	v_mfma_f32_16x16x32_bf16 v[32:35], v[186:189], v[202:205], v[32:35]
	s_waitcnt lgkmcnt(2)
	v_mfma_f32_16x16x32_bf16 v[28:31], v[156:159], v[206:209], v[28:31]
	v_mfma_f32_16x16x32_bf16 v[24:27], v[164:167], v[206:209], v[24:27]
	v_mfma_f32_16x16x32_bf16 v[20:23], v[172:175], v[206:209], v[20:23]
	v_mfma_f32_16x16x32_bf16 v[16:19], v[180:183], v[206:209], v[16:19]
	v_mfma_f32_16x16x32_bf16 v[28:31], v[160:163], v[210:213], v[28:31]
	v_mfma_f32_16x16x32_bf16 v[24:27], v[168:171], v[210:213], v[24:27]
	v_mfma_f32_16x16x32_bf16 v[20:23], v[176:179], v[210:213], v[20:23]
	v_mfma_f32_16x16x32_bf16 v[16:19], v[186:189], v[210:213], v[16:19]
	s_waitcnt lgkmcnt(0)
	v_mfma_f32_16x16x32_bf16 v[12:15], v[156:159], v[214:217], v[12:15]
	v_mfma_f32_16x16x32_bf16 v[8:11], v[164:167], v[214:217], v[8:11]
	v_mfma_f32_16x16x32_bf16 v[4:7], v[172:175], v[214:217], v[4:7]
	v_mfma_f32_16x16x32_bf16 v[0:3], v[180:183], v[214:217], v[0:3]
	v_mfma_f32_16x16x32_bf16 v[12:15], v[160:163], v[218:221], v[12:15]
	v_mfma_f32_16x16x32_bf16 v[8:11], v[168:171], v[218:221], v[8:11]
	v_mfma_f32_16x16x32_bf16 v[4:7], v[176:179], v[218:221], v[4:7]
	v_mfma_f32_16x16x32_bf16 v[0:3], v[186:189], v[218:221], v[0:3]
	s_waitcnt vmcnt(2)
	s_barrier
	s_setprio 0
	s_add_i32 s62, s53, s3
	v_lshl_add_u64 v[222:223], s[56:57], 0, v[130:131]
	s_mov_b32 m0, s62
	s_nop 0
	global_load_lds_dwordx4 v[222:223], off
	s_add_i32 m0, s62, 0x2000
	s_add_u32 s62, s56, 0x80000
	v_lshl_add_u64 v[224:225], s[56:57], 0, v[134:135]
	s_addc_u32 s63, s57, 0
	s_add_i32 s64, s55, s3
	global_load_lds_dwordx4 v[224:225], off
	v_lshl_add_u64 v[226:227], s[62:63], 0, v[130:131]
	s_mov_b32 m0, s64
	v_lshl_add_u64 v[228:229], s[58:59], 0, v[132:133]
	global_load_lds_dwordx4 v[226:227], off
	v_lshl_add_u64 v[226:227], s[62:63], 0, v[134:135]
	s_add_i32 m0, s64, 0x2000
	s_nop 0
	global_load_lds_dwordx4 v[226:227], off
	v_lshl_add_u64 v[226:227], s[58:59], 0, v[128:129]
	s_mov_b32 m0, s6
	s_nop 0
	global_load_lds_dwordx4 v[226:227], off
	s_mov_b32 m0, s7
	s_nop 0
	global_load_lds_dwordx4 v[228:229], off
	s_add_i32 s62, 0, 0x18000
	v_add_u32_e32 v155, s62, v150
	s_add_i32 s63, 0, 0x1c000
	ds_read_b128 v[156:159], v155
	ds_read_b128 v[160:163], v155 offset:1024
	ds_read_b128 v[164:167], v155 offset:2048
	ds_read_b128 v[168:171], v155 offset:3072
	v_add_u32_e32 v155, s63, v150
	ds_read_b128 v[172:175], v155
	ds_read_b128 v[176:179], v155 offset:1024
	ds_read_b128 v[180:183], v155 offset:2048
	ds_read_b128 v[186:189], v155 offset:3072
	ds_read_b128 v[190:193], v154 offset:32768
	ds_read_b128 v[194:197], v154 offset:33792
	ds_read_b128 v[198:201], v154 offset:34816
	ds_read_b128 v[202:205], v154 offset:35840
	ds_read_b128 v[206:209], v154 offset:36864
	ds_read_b128 v[210:213], v154 offset:37888
	ds_read_b128 v[214:217], v154 offset:38912
	ds_read_b128 v[218:221], v154 offset:39936
	s_waitcnt vmcnt(6)
	s_waitcnt lgkmcnt(0)
	s_setprio 1
	s_barrier
	v_mfma_f32_16x16x32_bf16 v[124:127], v[156:159], v[190:193], v[124:127]
	v_mfma_f32_16x16x32_bf16 v[120:123], v[164:167], v[190:193], v[120:123]
	s_add_u32 s58, s58, 0x80000
	s_addc_u32 s59, s59, 0
	v_mfma_f32_16x16x32_bf16 v[116:119], v[172:175], v[190:193], v[116:119]
	s_mov_b32 m0, s8
	v_lshl_add_u64 v[230:231], s[58:59], 0, v[128:129]
	v_mfma_f32_16x16x32_bf16 v[112:115], v[180:183], v[190:193], v[112:115]
	global_load_lds_dwordx4 v[230:231], off
	v_lshl_add_u64 v[230:231], s[58:59], 0, v[132:133]
	v_mfma_f32_16x16x32_bf16 v[124:127], v[160:163], v[194:197], v[124:127]
	s_mov_b32 m0, s9
	s_nop 0
	v_mfma_f32_16x16x32_bf16 v[120:123], v[168:171], v[194:197], v[120:123]
	global_load_lds_dwordx4 v[230:231], off
	v_mfma_f32_16x16x32_bf16 v[116:119], v[176:179], v[194:197], v[116:119]
	v_mfma_f32_16x16x32_bf16 v[112:115], v[186:189], v[194:197], v[112:115]
	ds_read_b128 v[190:193], v154 offset:49152
	ds_read_b128 v[194:197], v154 offset:50176
	v_mfma_f32_16x16x32_bf16 v[108:111], v[156:159], v[198:201], v[108:111]
	v_mfma_f32_16x16x32_bf16 v[104:107], v[164:167], v[198:201], v[104:107]
	v_mfma_f32_16x16x32_bf16 v[100:103], v[172:175], v[198:201], v[100:103]
	v_mfma_f32_16x16x32_bf16 v[96:99], v[180:183], v[198:201], v[96:99]
	v_mfma_f32_16x16x32_bf16 v[108:111], v[160:163], v[202:205], v[108:111]
	v_mfma_f32_16x16x32_bf16 v[104:107], v[168:171], v[202:205], v[104:107]
	v_mfma_f32_16x16x32_bf16 v[100:103], v[176:179], v[202:205], v[100:103]
	v_mfma_f32_16x16x32_bf16 v[96:99], v[186:189], v[202:205], v[96:99]
	ds_read_b128 v[198:201], v154 offset:51200
	ds_read_b128 v[202:205], v154 offset:52224
	v_mfma_f32_16x16x32_bf16 v[92:95], v[156:159], v[206:209], v[92:95]
	v_mfma_f32_16x16x32_bf16 v[88:91], v[164:167], v[206:209], v[88:91]
	v_mfma_f32_16x16x32_bf16 v[84:87], v[172:175], v[206:209], v[84:87]
	v_mfma_f32_16x16x32_bf16 v[80:83], v[180:183], v[206:209], v[80:83]
	v_mfma_f32_16x16x32_bf16 v[92:95], v[160:163], v[210:213], v[92:95]
	v_mfma_f32_16x16x32_bf16 v[88:91], v[168:171], v[210:213], v[88:91]
	v_mfma_f32_16x16x32_bf16 v[84:87], v[176:179], v[210:213], v[84:87]
	v_mfma_f32_16x16x32_bf16 v[80:83], v[186:189], v[210:213], v[80:83]
	ds_read_b128 v[206:209], v154 offset:53248
	ds_read_b128 v[210:213], v154 offset:54272
	v_mfma_f32_16x16x32_bf16 v[76:79], v[156:159], v[214:217], v[76:79]
	v_mfma_f32_16x16x32_bf16 v[72:75], v[164:167], v[214:217], v[72:75]
	v_mfma_f32_16x16x32_bf16 v[68:71], v[172:175], v[214:217], v[68:71]
	v_mfma_f32_16x16x32_bf16 v[64:67], v[180:183], v[214:217], v[64:67]
	v_mfma_f32_16x16x32_bf16 v[76:79], v[160:163], v[218:221], v[76:79]
	v_mfma_f32_16x16x32_bf16 v[72:75], v[168:171], v[218:221], v[72:75]
	v_mfma_f32_16x16x32_bf16 v[68:71], v[176:179], v[218:221], v[68:71]
	v_mfma_f32_16x16x32_bf16 v[64:67], v[186:189], v[218:221], v[64:67]
	ds_read_b128 v[214:217], v154 offset:55296
	ds_read_b128 v[218:221], v154 offset:56320
	s_waitcnt lgkmcnt(6)
; #define PG8_STAGE(bufoff, gbase, voff) do { _Pragma("unroll") for (int _i = 0; _i < 2; ++_i) \
;         __builtin_amdgcn_global_load_lds((const unsigned*)((const char*)(gbase) + (voff)[_i]), (PG8_LAS unsigned*)(lds + (bufoff) + ldsw + _i * 8192), 16, 0, 0); } while (0)
; #define PG8_LDA(dst, b, h) do { _Pragma("unroll") for (int m = 0; m < 4; ++m) _Pragma("unroll") for (int k = 0; k < 2; ++k) dst[m][k] = *(const PG8_LAS bf16x8*)(lds + PG8_SA(b, h) + aoff + m * 2048 + k * 1024); } while (0)
; #define PG8_LDB(dst, b, h) do { _Pragma("unroll") for (int n = 0; n < 2; ++n) _Pragma("unroll") for (int k = 0; k < 2; ++k) dst[n][k] = *(const PG8_LAS bf16x8*)(lds + PG8_SB(b, h) + boff + n * 2048 + k * 1024); } while (0)
; template <class Epi, class Sched, bool ALIGN_EPI = false, bool SP2 = false>
; __device__ __forceinline__ void gemm_phase(PG8_LAS unsigned char* lds, const Gemm g, const Sched& S, const Epi& E) {
;     ...
;         for (int t = 0; t < nt; t += 2) {
;             const bool last = (t == nt - 2);
;             const char* a1 = cA + (size_t)(t + 1) * kstA;
;             const char* a2 = last ? nA : cA + (size_t)(t + 2) * kstA; const char* b2 = last ? nB : cB + (size_t)(t + 2) * kstep;
;             const char* a3 = a2 + kstA; const char* b3 = b2 + kstep;
;             if (last && has_next) S.a_ready(nxt);
;             if constexpr (SP2) {
;             PG8_LDB(B0, 0, 0); PG8_LDB(B1, 0, 1); PG8_SCHED; PG8_LDA(At, 0, 0); PG8_STAGE(PG8_SA(1, 1), a1 + hstepA, voffA);
;             PG8_WAIT_V(8); PG8_WAIT_L(0); PG8_BAR; PG8_MMA(0, 0, At, B0); PG8_MMA(0, 1, At, B1); PG8_BAR; PG8_SCHED;
;             PG8_LDA(At, 0, 1); PG8_STAGE(PG8_SB(0, 0), b2, voffB); PG8_STAGE(PG8_SB(0, 1), b2 + hstepB, voffB); PG8_STAGE(PG8_SA(0, 0), a2, voffA);
;             PG8_WAIT_V(8); PG8_WAIT_L(0); PG8_BAR; PG8_MMA(1, 0, At, B0); PG8_MMA(1, 1, At, B1); PG8_BAR; PG8_SCHED;
;             PG8_LDB(B0, 1, 0); PG8_LDB(B1, 1, 1); PG8_SCHED; PG8_LDA(At, 1, 0); PG8_STAGE(PG8_SA(0, 1), a2 + hstepA, voffA);
;             PG8_WAIT_V(8); PG8_WAIT_L(0); PG8_BAR; PG8_MMA(0, 0, At, B0); PG8_MMA(0, 1, At, B1); PG8_BAR; PG8_SCHED;
;             PG8_LDA(At, 1, 1); PG8_STAGE(PG8_SB(1, 0), b3, voffB); PG8_STAGE(PG8_SB(1, 1), b3 + hstepB, voffB); PG8_STAGE(PG8_SA(1, 0), a3, voffA);
;             PG8_WAIT_V(8); PG8_WAIT_L(0); PG8_BAR; PG8_MMA(1, 0, At, B0); PG8_MMA(1, 1, At, B1); PG8_BAR; PG8_SCHED;
	v_mfma_f32_16x16x32_bf16 v[60:63], v[156:159], v[190:193], v[60:63]
	v_mfma_f32_16x16x32_bf16 v[56:59], v[164:167], v[190:193], v[56:59]
	v_mfma_f32_16x16x32_bf16 v[52:55], v[172:175], v[190:193], v[52:55]
	v_mfma_f32_16x16x32_bf16 v[48:51], v[180:183], v[190:193], v[48:51]
	v_mfma_f32_16x16x32_bf16 v[60:63], v[160:163], v[194:197], v[60:63]
	v_mfma_f32_16x16x32_bf16 v[56:59], v[168:171], v[194:197], v[56:59]
	v_mfma_f32_16x16x32_bf16 v[52:55], v[176:179], v[194:197], v[52:55]
	v_mfma_f32_16x16x32_bf16 v[48:51], v[186:189], v[194:197], v[48:51]
	s_waitcnt lgkmcnt(4)
	v_mfma_f32_16x16x32_bf16 v[44:47], v[156:159], v[198:201], v[44:47]
	v_mfma_f32_16x16x32_bf16 v[40:43], v[164:167], v[198:201], v[40:43]
	v_mfma_f32_16x16x32_bf16 v[36:39], v[172:175], v[198:201], v[36:39]
	v_mfma_f32_16x16x32_bf16 v[32:35], v[180:183], v[198:201], v[32:35]
	v_mfma_f32_16x16x32_bf16 v[44:47], v[160:163], v[202:205], v[44:47]
	v_mfma_f32_16x16x32_bf16 v[40:43], v[168:171], v[202:205], v[40:43]
	v_mfma_f32_16x16x32_bf16 v[36:39], v[176:179], v[202:205], v[36:39]
	v_mfma_f32_16x16x32_bf16 v[32:35], v[186:189], v[202:205], v[32:35]
	s_waitcnt lgkmcnt(2)
	v_mfma_f32_16x16x32_bf16 v[28:31], v[156:159], v[206:209], v[28:31]
	v_mfma_f32_16x16x32_bf16 v[24:27], v[164:167], v[206:209], v[24:27]
	v_mfma_f32_16x16x32_bf16 v[20:23], v[172:175], v[206:209], v[20:23]
	v_mfma_f32_16x16x32_bf16 v[16:19], v[180:183], v[206:209], v[16:19]
	v_mfma_f32_16x16x32_bf16 v[28:31], v[160:163], v[210:213], v[28:31]
	v_mfma_f32_16x16x32_bf16 v[24:27], v[168:171], v[210:213], v[24:27]
	v_mfma_f32_16x16x32_bf16 v[20:23], v[176:179], v[210:213], v[20:23]
	v_mfma_f32_16x16x32_bf16 v[16:19], v[186:189], v[210:213], v[16:19]
	s_waitcnt lgkmcnt(0)
	v_mfma_f32_16x16x32_bf16 v[12:15], v[156:159], v[214:217], v[12:15]
	v_mfma_f32_16x16x32_bf16 v[8:11], v[164:167], v[214:217], v[8:11]
	v_mfma_f32_16x16x32_bf16 v[4:7], v[172:175], v[214:217], v[4:7]
	v_mfma_f32_16x16x32_bf16 v[0:3], v[180:183], v[214:217], v[0:3]
	v_mfma_f32_16x16x32_bf16 v[12:15], v[160:163], v[218:221], v[12:15]
	v_mfma_f32_16x16x32_bf16 v[8:11], v[168:171], v[218:221], v[8:11]
	v_mfma_f32_16x16x32_bf16 v[4:7], v[176:179], v[218:221], v[4:7]
	v_mfma_f32_16x16x32_bf16 v[0:3], v[186:189], v[218:221], v[0:3]
	s_waitcnt vmcnt(2)
	s_barrier
	s_setprio 0
	s_add_i32 s61, s61, 2
	s_add_u32 s50, s50, 0x100
	s_addc_u32 s51, s51, 0
	s_add_u32 s41, s41, 0x100
	s_addc_u32 s43, s43, 0
	s_cmp_gt_u32 s61, 29
	s_cbranch_scc0 .Lmy_m64_0_w0_top
	s_add_i32 s58, s62, s3
	v_lshl_add_u64 v[222:223], v[222:223], 0, s[36:37]
	s_mov_b32 m0, s58
	s_nop 0
	global_load_lds_dwordx4 v[222:223], off
	s_add_i32 m0, s58, 0x2000
	s_add_u32 s56, s56, 0x80080
	v_lshl_add_u64 v[222:223], v[224:225], 0, s[36:37]
	s_addc_u32 s57, s57, 0
	s_add_i32 s58, s63, s3
	global_load_lds_dwordx4 v[222:223], off
	v_lshl_add_u64 v[222:223], s[56:57], 0, v[130:131]
	s_mov_b32 m0, s58
	s_nop 0
	global_load_lds_dwordx4 v[222:223], off
	v_lshl_add_u64 v[222:223], s[56:57], 0, v[134:135]
	s_add_i32 m0, s58, 0x2000
	s_nop 0
	global_load_lds_dwordx4 v[222:223], off
	v_lshl_add_u64 v[222:223], v[226:227], 0, s[36:37]
	s_mov_b32 m0, s44
	s_nop 0
	global_load_lds_dwordx4 v[222:223], off
	v_lshl_add_u64 v[222:223], v[228:229], 0, s[36:37]
	s_mov_b32 m0, s45
	s_nop 0
	global_load_lds_dwordx4 v[222:223], off
	s_branch .Lmy_m64_0_exit
.Lmy_m64_0_w1_top:
	ds_read_b128 v[156:159], v152
	ds_read_b128 v[160:163], v152 offset:1024
	ds_read_b128 v[164:167], v152 offset:2048
	ds_read_b128 v[168:171], v152 offset:3072
	ds_read_b128 v[172:175], v153
	ds_read_b128 v[176:179], v153 offset:1024
	ds_read_b128 v[180:183], v153 offset:2048
	ds_read_b128 v[186:189], v153 offset:3072
	s_add_u32 s56, s50, 0xfff80080
	s_addc_u32 s57, s51, -1
	s_cmp_eq_u32 s61, 28
	s_cselect_b32 s59, s4, s57
	s_cselect_b32 s58, s5, s56
	s_cselect_b32 s57, s12, s43
	s_cselect_b32 s56, s13, s41
	v_lshl_add_u64 v[222:223], s[50:51], 0, v[142:143]
	s_add_i32 m0, s6, 0xc000
	ds_read_b128 v[190:193], v154
	ds_read_b128 v[194:197], v154 offset:1024
	ds_read_b128 v[198:201], v154 offset:2048
	ds_read_b128 v[202:205], v154 offset:3072
	ds_read_b128 v[206:209], v154 offset:4096
	ds_read_b128 v[210:213], v154 offset:5120
	ds_read_b128 v[214:217], v154 offset:6144
	ds_read_b128 v[218:221], v154 offset:7168
	global_load_lds_dwordx4 v[222:223], off
	v_lshl_add_u64 v[222:223], s[50:51], 0, v[144:145]
	s_add_i32 m0, s6, 0xe000
	s_nop 0
	global_load_lds_dwordx4 v[222:223], off
	s_waitcnt vmcnt(2)
	s_waitcnt lgkmcnt(0)
	s_setprio 1
	s_barrier
; #define PG8_STAGE(bufoff, gbase, voff) do { _Pragma("unroll") for (int _i = 0; _i < 2; ++_i) \
;         __builtin_amdgcn_global_load_lds((const unsigned*)((const char*)(gbase) + (voff)[_i]), (PG8_LAS unsigned*)(lds + (bufoff) + ldsw + _i * 8192), 16, 0, 0); } while (0)
; #define PG8_LDA(dst, b, h) do { _Pragma("unroll") for (int m = 0; m < 4; ++m) _Pragma("unroll") for (int k = 0; k < 2; ++k) dst[m][k] = *(const PG8_LAS bf16x8*)(lds + PG8_SA(b, h) + aoff + m * 2048 + k * 1024); } while (0)
; #define PG8_LDB(dst, b, h) do { _Pragma("unroll") for (int n = 0; n < 2; ++n) _Pragma("unroll") for (int k = 0; k < 2; ++k) dst[n][k] = *(const PG8_LAS bf16x8*)(lds + PG8_SB(b, h) + boff + n * 2048 + k * 1024); } while (0)
; #define PG8_MMA(ai, bj, At, Bt) do { __builtin_amdgcn_s_setprio(1); _Pragma("unroll") for (int m = 0; m < 4; ++m) _Pragma("unroll") for (int n = 0; n < 2; ++n) _Pragma("unroll") for (int k = 0; k < 2; ++k) \
;         acc[ai][bj][m][n] = __builtin_amdgcn_mfma_f32_16x16x32_bf16(Bt[n][k], At[m][k], acc[ai][bj][m][n], 0, 0, 0); __builtin_amdgcn_s_setprio(0); } while (0)
; template <class Epi, class Sched, bool ALIGN_EPI = false, bool SP2 = false>
; __device__ __forceinline__ void gemm_phase(PG8_LAS unsigned char* lds, const Gemm g, const Sched& S, const Epi& E) {
;     ...
;             if constexpr (SP2) {
;             PG8_LDB(B0, 0, 0); PG8_LDB(B1, 0, 1); PG8_SCHED; PG8_LDA(At, 0, 0); PG8_STAGE(PG8_SA(1, 1), a1 + hstepA, voffA);
;             PG8_WAIT_V(8); PG8_WAIT_L(0); PG8_BAR; PG8_MMA(0, 0, At, B0); PG8_MMA(0, 1, At, B1); PG8_BAR; PG8_SCHED;
;             PG8_LDA(At, 0, 1); PG8_STAGE(PG8_SB(0, 0), b2, voffB); PG8_STAGE(PG8_SB(0, 1), b2 + hstepB, voffB); PG8_STAGE(PG8_SA(0, 0), a2, voffA);
;             PG8_WAIT_V(8); PG8_WAIT_L(0); PG8_BAR; PG8_MMA(1, 0, At, B0); PG8_MMA(1, 1, At, B1); PG8_BAR; PG8_SCHED;
;             PG8_LDB(B0, 1, 0); PG8_LDB(B1, 1, 1); PG8_SCHED; PG8_LDA(At, 1, 0); PG8_STAGE(PG8_SA(0, 1), a2 + hstepA, voffA);
;             PG8_WAIT_V(8); PG8_WAIT_L(0); PG8_BAR; PG8_MMA(0, 0, At, B0); PG8_MMA(0, 1, At, B1); PG8_BAR; PG8_SCHED;
;             PG8_LDA(At, 1, 1); PG8_STAGE(PG8_SB(1, 0), b3, voffB); PG8_STAGE(PG8_SB(1, 1), b3 + hstepB, voffB); PG8_STAGE(PG8_SA(1, 0), a3, voffA);
;             PG8_WAIT_V(8); PG8_WAIT_L(0); PG8_BAR; PG8_MMA(1, 0, At, B0); PG8_MMA(1, 1, At, B1); PG8_BAR; PG8_SCHED;
	v_mfma_f32_16x16x32_bf16 v[124:127], v[156:159], v[190:193], v[124:127]
	v_mfma_f32_16x16x32_bf16 v[120:123], v[164:167], v[190:193], v[120:123]
	s_add_i32 s62, s53, s3
	v_lshl_add_u64 v[222:223], s[56:57], 0, v[130:131]
	v_mfma_f32_16x16x32_bf16 v[116:119], v[172:175], v[190:193], v[116:119]
	s_mov_b32 m0, s62
	s_nop 0
	global_load_lds_dwordx4 v[222:223], off
	v_mfma_f32_16x16x32_bf16 v[112:115], v[180:183], v[190:193], v[112:115]
	s_add_i32 m0, s62, 0x2000
	s_add_u32 s62, s56, 0x80000
	v_mfma_f32_16x16x32_bf16 v[124:127], v[160:163], v[194:197], v[124:127]
	v_lshl_add_u64 v[224:225], s[56:57], 0, v[134:135]
	s_addc_u32 s63, s57, 0
	v_mfma_f32_16x16x32_bf16 v[120:123], v[168:171], v[194:197], v[120:123]
	s_add_i32 s64, s55, s3
	global_load_lds_dwordx4 v[224:225], off
	v_mfma_f32_16x16x32_bf16 v[116:119], v[176:179], v[194:197], v[116:119]
	v_lshl_add_u64 v[226:227], s[62:63], 0, v[130:131]
	s_mov_b32 m0, s64
	v_mfma_f32_16x16x32_bf16 v[112:115], v[186:189], v[194:197], v[112:115]
	v_lshl_add_u64 v[228:229], s[58:59], 0, v[132:133]
	global_load_lds_dwordx4 v[226:227], off
	ds_read_b128 v[190:193], v154 offset:16384
	ds_read_b128 v[194:197], v154 offset:17408
	v_mfma_f32_16x16x32_bf16 v[108:111], v[156:159], v[198:201], v[108:111]
	v_lshl_add_u64 v[226:227], s[62:63], 0, v[134:135]
	s_add_i32 m0, s64, 0x2000
	v_mfma_f32_16x16x32_bf16 v[104:107], v[164:167], v[198:201], v[104:107]
	s_nop 0
	global_load_lds_dwordx4 v[226:227], off
	v_mfma_f32_16x16x32_bf16 v[100:103], v[172:175], v[198:201], v[100:103]
	v_lshl_add_u64 v[226:227], s[58:59], 0, v[128:129]
	s_mov_b32 m0, s6
	v_mfma_f32_16x16x32_bf16 v[96:99], v[180:183], v[198:201], v[96:99]
	s_nop 0
	global_load_lds_dwordx4 v[226:227], off
	v_mfma_f32_16x16x32_bf16 v[108:111], v[160:163], v[202:205], v[108:111]
	s_mov_b32 m0, s7
	s_nop 0
	v_mfma_f32_16x16x32_bf16 v[104:107], v[168:171], v[202:205], v[104:107]
	global_load_lds_dwordx4 v[228:229], off
	v_mfma_f32_16x16x32_bf16 v[100:103], v[176:179], v[202:205], v[100:103]
	v_mfma_f32_16x16x32_bf16 v[96:99], v[186:189], v[202:205], v[96:99]
	ds_read_b128 v[198:201], v154 offset:18432
	ds_read_b128 v[202:205], v154 offset:19456
	v_mfma_f32_16x16x32_bf16 v[92:95], v[156:159], v[206:209], v[92:95]
	v_mfma_f32_16x16x32_bf16 v[88:91], v[164:167], v[206:209], v[88:91]
	v_mfma_f32_16x16x32_bf16 v[84:87], v[172:175], v[206:209], v[84:87]
	v_mfma_f32_16x16x32_bf16 v[80:83], v[180:183], v[206:209], v[80:83]
	v_mfma_f32_16x16x32_bf16 v[92:95], v[160:163], v[210:213], v[92:95]
	v_mfma_f32_16x16x32_bf16 v[88:91], v[168:171], v[210:213], v[88:91]
	v_mfma_f32_16x16x32_bf16 v[84:87], v[176:179], v[210:213], v[84:87]
	v_mfma_f32_16x16x32_bf16 v[80:83], v[186:189], v[210:213], v[80:83]
	ds_read_b128 v[206:209], v154 offset:20480
	ds_read_b128 v[210:213], v154 offset:21504
	v_mfma_f32_16x16x32_bf16 v[76:79], v[156:159], v[214:217], v[76:79]
	v_mfma_f32_16x16x32_bf16 v[72:75], v[164:167], v[214:217], v[72:75]
	v_mfma_f32_16x16x32_bf16 v[68:71], v[172:175], v[214:217], v[68:71]
	v_mfma_f32_16x16x32_bf16 v[64:67], v[180:183], v[214:217], v[64:67]
	v_mfma_f32_16x16x32_bf16 v[76:79], v[160:163], v[218:221], v[76:79]
	v_mfma_f32_16x16x32_bf16 v[72:75], v[168:171], v[218:221], v[72:75]
	v_mfma_f32_16x16x32_bf16 v[68:71], v[176:179], v[218:221], v[68:71]
	v_mfma_f32_16x16x32_bf16 v[64:67], v[186:189], v[218:221], v[64:67]
	ds_read_b128 v[214:217], v154 offset:22528
	ds_read_b128 v[218:221], v154 offset:23552
	s_waitcnt lgkmcnt(6)
	v_mfma_f32_16x16x32_bf16 v[60:63], v[156:159], v[190:193], v[60:63]
	v_mfma_f32_16x16x32_bf16 v[56:59], v[164:167], v[190:193], v[56:59]
	v_mfma_f32_16x16x32_bf16 v[52:55], v[172:175], v[190:193], v[52:55]
	v_mfma_f32_16x16x32_bf16 v[48:51], v[180:183], v[190:193], v[48:51]
	v_mfma_f32_16x16x32_bf16 v[60:63], v[160:163], v[194:197], v[60:63]
	v_mfma_f32_16x16x32_bf16 v[56:59], v[168:171], v[194:197], v[56:59]
	v_mfma_f32_16x16x32_bf16 v[52:55], v[176:179], v[194:197], v[52:55]
	v_mfma_f32_16x16x32_bf16 v[48:51], v[186:189], v[194:197], v[48:51]
	s_waitcnt lgkmcnt(4)
	v_mfma_f32_16x16x32_bf16 v[44:47], v[156:159], v[198:201], v[44:47]
	v_mfma_f32_16x16x32_bf16 v[40:43], v[164:167], v[198:201], v[40:43]
	v_mfma_f32_16x16x32_bf16 v[36:39], v[172:175], v[198:201], v[36:39]
	v_mfma_f32_16x16x32_bf16 v[32:35], v[180:183], v[198:201], v[32:35]
	v_mfma_f32_16x16x32_bf16 v[44:47], v[160:163], v[202:205], v[44:47]
	v_mfma_f32_16x16x32_bf16 v[40:43], v[168:171], v[202:205], v[40:43]
	v_mfma_f32_16x16x32_bf16 v[36:39], v[176:179], v[202:205], v[36:39]
	v_mfma_f32_16x16x32_bf16 v[32:35], v[186:189], v[202:205], v[32:35]
	s_waitcnt lgkmcnt(2)
	v_mfma_f32_16x16x32_bf16 v[28:31], v[156:159], v[206:209], v[28:31]
	v_mfma_f32_16x16x32_bf16 v[24:27], v[164:167], v[206:209], v[24:27]
	v_mfma_f32_16x16x32_bf16 v[20:23], v[172:175], v[206:209], v[20:23]
	v_mfma_f32_16x16x32_bf16 v[16:19], v[180:183], v[206:209], v[16:19]
	v_mfma_f32_16x16x32_bf16 v[28:31], v[160:163], v[210:213], v[28:31]
	v_mfma_f32_16x16x32_bf16 v[24:27], v[168:171], v[210:213], v[24:27]
	v_mfma_f32_16x16x32_bf16 v[20:23], v[176:179], v[210:213], v[20:23]
	v_mfma_f32_16x16x32_bf16 v[16:19], v[186:189], v[210:213], v[16:19]
	s_waitcnt lgkmcnt(0)
	v_mfma_f32_16x16x32_bf16 v[12:15], v[156:159], v[214:217], v[12:15]
	v_mfma_f32_16x16x32_bf16 v[8:11], v[164:167], v[214:217], v[8:11]
	v_mfma_f32_16x16x32_bf16 v[4:7], v[172:175], v[214:217], v[4:7]
	v_mfma_f32_16x16x32_bf16 v[0:3], v[180:183], v[214:217], v[0:3]
	v_mfma_f32_16x16x32_bf16 v[12:15], v[160:163], v[218:221], v[12:15]
	v_mfma_f32_16x16x32_bf16 v[8:11], v[168:171], v[218:221], v[8:11]
	v_mfma_f32_16x16x32_bf16 v[4:7], v[176:179], v[218:221], v[4:7]
	v_mfma_f32_16x16x32_bf16 v[0:3], v[186:189], v[218:221], v[0:3]
	s_waitcnt vmcnt(6)
	s_barrier
; #define PG8_STAGE(bufoff, gbase, voff) do { _Pragma("unroll") for (int _i = 0; _i < 2; ++_i) \
;         __builtin_amdgcn_global_load_lds((const unsigned*)((const char*)(gbase) + (voff)[_i]), (PG8_LAS unsigned*)(lds + (bufoff) + ldsw + _i * 8192), 16, 0, 0); } while (0)
; #define PG8_LDA(dst, b, h) do { _Pragma("unroll") for (int m = 0; m < 4; ++m) _Pragma("unroll") for (int k = 0; k < 2; ++k) dst[m][k] = *(const PG8_LAS bf16x8*)(lds + PG8_SA(b, h) + aoff + m * 2048 + k * 1024); } while (0)
; #define PG8_LDB(dst, b, h) do { _Pragma("unroll") for (int n = 0; n < 2; ++n) _Pragma("unroll") for (int k = 0; k < 2; ++k) dst[n][k] = *(const PG8_LAS bf16x8*)(lds + PG8_SB(b, h) + boff + n * 2048 + k * 1024); } while (0)
; #define PG8_MMA(ai, bj, At, Bt) do { __builtin_amdgcn_s_setprio(1); _Pragma("unroll") for (int m = 0; m < 4; ++m) _Pragma("unroll") for (int n = 0; n < 2; ++n) _Pragma("unroll") for (int k = 0; k < 2; ++k) \
;         acc[ai][bj][m][n] = __builtin_amdgcn_mfma_f32_16x16x32_bf16(Bt[n][k], At[m][k], acc[ai][bj][m][n], 0, 0, 0); __builtin_amdgcn_s_setprio(0); } while (0)
; #define PG8_WAIT_V(n) asm volatile("s_waitcnt vmcnt(" #n ")" ::: "memory")
; #define PG8_WAIT_L(n) asm volatile("s_waitcnt lgkmcnt(" #n ")" ::: "memory")
; #define PG8_BAR __builtin_amdgcn_s_barrier()
; #define PG8_SCHED __builtin_amdgcn_sched_barrier(0)
; template <class Epi, class Sched, bool ALIGN_EPI = false, bool SP2 = false>
; __device__ __forceinline__ void gemm_phase(PG8_LAS unsigned char* lds, const Gemm g, const Sched& S, const Epi& E) {
;     ...
;             PG8_LDB(B0, 1, 0); PG8_LDB(B1, 1, 1); PG8_SCHED; PG8_LDA(At, 1, 0); PG8_STAGE(PG8_SA(0, 1), a2 + hstepA, voffA);
;             PG8_WAIT_V(8); PG8_WAIT_L(0); PG8_BAR; PG8_MMA(0, 0, At, B0); PG8_MMA(0, 1, At, B1); PG8_BAR; PG8_SCHED;
	s_setprio 0
	s_add_i32 s62, 0, 0x18000
	v_add_u32_e32 v155, s62, v150
	s_add_i32 s63, 0, 0x1c000
	ds_read_b128 v[156:159], v155
	ds_read_b128 v[160:163], v155 offset:1024
	ds_read_b128 v[164:167], v155 offset:2048
	ds_read_b128 v[168:171], v155 offset:3072
	v_add_u32_e32 v155, s63, v150
	ds_read_b128 v[172:175], v155
	ds_read_b128 v[176:179], v155 offset:1024
	ds_read_b128 v[180:183], v155 offset:2048
	ds_read_b128 v[186:189], v155 offset:3072
	s_add_u32 s58, s58, 0x80000
	s_addc_u32 s59, s59, 0
	s_mov_b32 m0, s8
	v_lshl_add_u64 v[230:231], s[58:59], 0, v[128:129]
	ds_read_b128 v[190:193], v154 offset:32768
	ds_read_b128 v[194:197], v154 offset:33792
	ds_read_b128 v[198:201], v154 offset:34816
	ds_read_b128 v[202:205], v154 offset:35840
	ds_read_b128 v[206:209], v154 offset:36864
	ds_read_b128 v[210:213], v154 offset:37888
	ds_read_b128 v[214:217], v154 offset:38912
	ds_read_b128 v[218:221], v154 offset:39936
	global_load_lds_dwordx4 v[230:231], off
	v_lshl_add_u64 v[230:231], s[58:59], 0, v[132:133]
	s_mov_b32 m0, s9
	s_nop 0
	global_load_lds_dwordx4 v[230:231], off
	s_waitcnt vmcnt(2)
	s_waitcnt lgkmcnt(0)
	s_setprio 1
	s_barrier
; #define PG8_STAGE(bufoff, gbase, voff) do { _Pragma("unroll") for (int _i = 0; _i < 2; ++_i) \
;         __builtin_amdgcn_global_load_lds((const unsigned*)((const char*)(gbase) + (voff)[_i]), (PG8_LAS unsigned*)(lds + (bufoff) + ldsw + _i * 8192), 16, 0, 0); } while (0)
; #define PG8_LDA(dst, b, h) do { _Pragma("unroll") for (int m = 0; m < 4; ++m) _Pragma("unroll") for (int k = 0; k < 2; ++k) dst[m][k] = *(const PG8_LAS bf16x8*)(lds + PG8_SA(b, h) + aoff + m * 2048 + k * 1024); } while (0)
; #define PG8_LDB(dst, b, h) do { _Pragma("unroll") for (int n = 0; n < 2; ++n) _Pragma("unroll") for (int k = 0; k < 2; ++k) dst[n][k] = *(const PG8_LAS bf16x8*)(lds + PG8_SB(b, h) + boff + n * 2048 + k * 1024); } while (0)
; #define PG8_WAIT_V(n) asm volatile("s_waitcnt vmcnt(" #n ")" ::: "memory")
; #define PG8_WAIT_L(n) asm volatile("s_waitcnt lgkmcnt(" #n ")" ::: "memory")
; #define PG8_BAR __builtin_amdgcn_s_barrier()
; #define PG8_SCHED __builtin_amdgcn_sched_barrier(0)
; template <class Epi, class Sched, bool ALIGN_EPI = false, bool SP2 = false>
; __device__ __forceinline__ void gemm_phase(PG8_LAS unsigned char* lds, const Gemm g, const Sched& S, const Epi& E) {
;     ...
;             if constexpr (SP2) {
;             PG8_LDB(B0, 0, 0); PG8_LDB(B1, 0, 1); PG8_SCHED; PG8_LDA(At, 0, 0); PG8_STAGE(PG8_SA(1, 1), a1 + hstepA, voffA);
;             PG8_WAIT_V(8); PG8_WAIT_L(0); PG8_BAR; PG8_MMA(0, 0, At, B0); PG8_MMA(0, 1, At, B1); PG8_BAR; PG8_SCHED;
;             PG8_LDA(At, 0, 1); PG8_STAGE(PG8_SB(0, 0), b2, voffB); PG8_STAGE(PG8_SB(0, 1), b2 + hstepB, voffB); PG8_STAGE(PG8_SA(0, 0), a2, voffA);
;             PG8_WAIT_V(8); PG8_WAIT_L(0); PG8_BAR; PG8_MMA(1, 0, At, B0); PG8_MMA(1, 1, At, B1); PG8_BAR; PG8_SCHED;
;             PG8_LDB(B0, 1, 0); PG8_LDB(B1, 1, 1); PG8_SCHED; PG8_LDA(At, 1, 0); PG8_STAGE(PG8_SA(0, 1), a2 + hstepA, voffA);
;             PG8_WAIT_V(8); PG8_WAIT_L(0); PG8_BAR; PG8_MMA(0, 0, At, B0); PG8_MMA(0, 1, At, B1); PG8_BAR; PG8_SCHED;
;             PG8_LDA(At, 1, 1); PG8_STAGE(PG8_SB(1, 0), b3, voffB); PG8_STAGE(PG8_SB(1, 1), b3 + hstepB, voffB); PG8_STAGE(PG8_SA(1, 0), a3, voffA);
;             PG8_WAIT_V(8); PG8_WAIT_L(0); PG8_BAR; PG8_MMA(1, 0, At, B0); PG8_MMA(1, 1, At, B1); PG8_BAR; PG8_SCHED;
;     ...
;         if constexpr (ALIGN_EPI) { if (wr == 0) PG8_BAR; }
;         if constexpr (!Epi::AFTER_DRAIN) { E(acc, cur, wr, wc, fr, fq); S.done(cur); }
	v_mfma_f32_16x16x32_bf16 v[124:127], v[156:159], v[190:193], v[124:127]
	v_mfma_f32_16x16x32_bf16 v[120:123], v[164:167], v[190:193], v[120:123]
	s_add_i32 s58, s62, s3
	v_lshl_add_u64 v[222:223], v[222:223], 0, s[36:37]
	v_mfma_f32_16x16x32_bf16 v[116:119], v[172:175], v[190:193], v[116:119]
	s_mov_b32 m0, s58
	s_nop 0
	global_load_lds_dwordx4 v[222:223], off
	v_mfma_f32_16x16x32_bf16 v[112:115], v[180:183], v[190:193], v[112:115]
	s_add_i32 m0, s58, 0x2000
	s_add_u32 s56, s56, 0x80080
	v_mfma_f32_16x16x32_bf16 v[124:127], v[160:163], v[194:197], v[124:127]
	v_lshl_add_u64 v[222:223], v[224:225], 0, s[36:37]
	s_addc_u32 s57, s57, 0
	v_mfma_f32_16x16x32_bf16 v[120:123], v[168:171], v[194:197], v[120:123]
	s_add_i32 s58, s63, s3
	global_load_lds_dwordx4 v[222:223], off
	v_mfma_f32_16x16x32_bf16 v[116:119], v[176:179], v[194:197], v[116:119]
	v_lshl_add_u64 v[222:223], s[56:57], 0, v[130:131]
	s_mov_b32 m0, s58
	v_mfma_f32_16x16x32_bf16 v[112:115], v[186:189], v[194:197], v[112:115]
	s_nop 0
	global_load_lds_dwordx4 v[222:223], off
	ds_read_b128 v[190:193], v154 offset:49152
	ds_read_b128 v[194:197], v154 offset:50176
	v_mfma_f32_16x16x32_bf16 v[108:111], v[156:159], v[198:201], v[108:111]
	v_lshl_add_u64 v[222:223], s[56:57], 0, v[134:135]
	s_add_i32 m0, s58, 0x2000
	v_mfma_f32_16x16x32_bf16 v[104:107], v[164:167], v[198:201], v[104:107]
	s_nop 0
	global_load_lds_dwordx4 v[222:223], off
	v_mfma_f32_16x16x32_bf16 v[100:103], v[172:175], v[198:201], v[100:103]
	v_lshl_add_u64 v[222:223], v[226:227], 0, s[36:37]
	s_mov_b32 m0, s44
	v_mfma_f32_16x16x32_bf16 v[96:99], v[180:183], v[198:201], v[96:99]
	s_nop 0
	global_load_lds_dwordx4 v[222:223], off
	v_mfma_f32_16x16x32_bf16 v[108:111], v[160:163], v[202:205], v[108:111]
	v_lshl_add_u64 v[222:223], v[228:229], 0, s[36:37]
	s_mov_b32 m0, s45
	v_mfma_f32_16x16x32_bf16 v[104:107], v[168:171], v[202:205], v[104:107]
	s_nop 0
	global_load_lds_dwordx4 v[222:223], off
	v_mfma_f32_16x16x32_bf16 v[100:103], v[176:179], v[202:205], v[100:103]
	v_mfma_f32_16x16x32_bf16 v[96:99], v[186:189], v[202:205], v[96:99]
	ds_read_b128 v[198:201], v154 offset:51200
	ds_read_b128 v[202:205], v154 offset:52224
	v_mfma_f32_16x16x32_bf16 v[92:95], v[156:159], v[206:209], v[92:95]
	v_mfma_f32_16x16x32_bf16 v[88:91], v[164:167], v[206:209], v[88:91]
	v_mfma_f32_16x16x32_bf16 v[84:87], v[172:175], v[206:209], v[84:87]
	v_mfma_f32_16x16x32_bf16 v[80:83], v[180:183], v[206:209], v[80:83]
	v_mfma_f32_16x16x32_bf16 v[92:95], v[160:163], v[210:213], v[92:95]
	v_mfma_f32_16x16x32_bf16 v[88:91], v[168:171], v[210:213], v[88:91]
	v_mfma_f32_16x16x32_bf16 v[84:87], v[176:179], v[210:213], v[84:87]
	v_mfma_f32_16x16x32_bf16 v[80:83], v[186:189], v[210:213], v[80:83]
	ds_read_b128 v[206:209], v154 offset:53248
	ds_read_b128 v[210:213], v154 offset:54272
	v_mfma_f32_16x16x32_bf16 v[76:79], v[156:159], v[214:217], v[76:79]
	v_mfma_f32_16x16x32_bf16 v[72:75], v[164:167], v[214:217], v[72:75]
	v_mfma_f32_16x16x32_bf16 v[68:71], v[172:175], v[214:217], v[68:71]
	v_mfma_f32_16x16x32_bf16 v[64:67], v[180:183], v[214:217], v[64:67]
	v_mfma_f32_16x16x32_bf16 v[76:79], v[160:163], v[218:221], v[76:79]
	v_mfma_f32_16x16x32_bf16 v[72:75], v[168:171], v[218:221], v[72:75]
	v_mfma_f32_16x16x32_bf16 v[68:71], v[176:179], v[218:221], v[68:71]
	v_mfma_f32_16x16x32_bf16 v[64:67], v[186:189], v[218:221], v[64:67]
	ds_read_b128 v[214:217], v154 offset:55296
	ds_read_b128 v[218:221], v154 offset:56320
	s_waitcnt lgkmcnt(6)
	v_mfma_f32_16x16x32_bf16 v[60:63], v[156:159], v[190:193], v[60:63]
	v_mfma_f32_16x16x32_bf16 v[56:59], v[164:167], v[190:193], v[56:59]
	v_mfma_f32_16x16x32_bf16 v[52:55], v[172:175], v[190:193], v[52:55]
	v_mfma_f32_16x16x32_bf16 v[48:51], v[180:183], v[190:193], v[48:51]
	v_mfma_f32_16x16x32_bf16 v[60:63], v[160:163], v[194:197], v[60:63]
	v_mfma_f32_16x16x32_bf16 v[56:59], v[168:171], v[194:197], v[56:59]
	v_mfma_f32_16x16x32_bf16 v[52:55], v[176:179], v[194:197], v[52:55]
	v_mfma_f32_16x16x32_bf16 v[48:51], v[186:189], v[194:197], v[48:51]
	s_waitcnt lgkmcnt(4)
	v_mfma_f32_16x16x32_bf16 v[44:47], v[156:159], v[198:201], v[44:47]
	v_mfma_f32_16x16x32_bf16 v[40:43], v[164:167], v[198:201], v[40:43]
	v_mfma_f32_16x16x32_bf16 v[36:39], v[172:175], v[198:201], v[36:39]
	v_mfma_f32_16x16x32_bf16 v[32:35], v[180:183], v[198:201], v[32:35]
	v_mfma_f32_16x16x32_bf16 v[44:47], v[160:163], v[202:205], v[44:47]
	v_mfma_f32_16x16x32_bf16 v[40:43], v[168:171], v[202:205], v[40:43]
	v_mfma_f32_16x16x32_bf16 v[36:39], v[176:179], v[202:205], v[36:39]
	v_mfma_f32_16x16x32_bf16 v[32:35], v[186:189], v[202:205], v[32:35]
	s_waitcnt lgkmcnt(2)
	v_mfma_f32_16x16x32_bf16 v[28:31], v[156:159], v[206:209], v[28:31]
	v_mfma_f32_16x16x32_bf16 v[24:27], v[164:167], v[206:209], v[24:27]
	v_mfma_f32_16x16x32_bf16 v[20:23], v[172:175], v[206:209], v[20:23]
	v_mfma_f32_16x16x32_bf16 v[16:19], v[180:183], v[206:209], v[16:19]
	v_mfma_f32_16x16x32_bf16 v[28:31], v[160:163], v[210:213], v[28:31]
	v_mfma_f32_16x16x32_bf16 v[24:27], v[168:171], v[210:213], v[24:27]
	v_mfma_f32_16x16x32_bf16 v[20:23], v[176:179], v[210:213], v[20:23]
	v_mfma_f32_16x16x32_bf16 v[16:19], v[186:189], v[210:213], v[16:19]
	s_waitcnt lgkmcnt(0)
	v_mfma_f32_16x16x32_bf16 v[12:15], v[156:159], v[214:217], v[12:15]
	v_mfma_f32_16x16x32_bf16 v[8:11], v[164:167], v[214:217], v[8:11]
	v_mfma_f32_16x16x32_bf16 v[4:7], v[172:175], v[214:217], v[4:7]
	v_mfma_f32_16x16x32_bf16 v[0:3], v[180:183], v[214:217], v[0:3]
	v_mfma_f32_16x16x32_bf16 v[12:15], v[160:163], v[218:221], v[12:15]
	v_mfma_f32_16x16x32_bf16 v[8:11], v[168:171], v[218:221], v[8:11]
	v_mfma_f32_16x16x32_bf16 v[4:7], v[176:179], v[218:221], v[4:7]
	v_mfma_f32_16x16x32_bf16 v[0:3], v[186:189], v[218:221], v[0:3]
	s_waitcnt vmcnt(6)
	s_barrier
	s_setprio 0
	s_add_i32 s61, s61, 2
	s_add_u32 s50, s50, 0x100
	s_addc_u32 s51, s51, 0
	s_add_u32 s41, s41, 0x100
	s_addc_u32 s43, s43, 0
	s_cmp_gt_u32 s61, 29
	s_cbranch_scc0 .Lmy_m64_0_w1_top
.Lmy_m64_0_exit:
	s_and_b64 vcc, exec, s[38:39]
	s_cbranch_vccz .LBB0_303
	s_barrier
